# GLA prompt chain: LDS fragment reads batched ahead of MFMAs, q fragments and decay scalars read once per step
# speedup vs baseline: 1.0721x; 1.0005x over previous
; #define LAS __attribute__((address_space(3)))
; __device__ __forceinline__ void gla_chain(int wv, const Args& A, LAS unsigned char* lds, int cidx0, int nsteps, int h, int sl, const float* S0, float* Sout) {
;     ...
;         __syncthreads();
; #pragma unroll
;         for (int vbl = 0; vbl < 4; ++vbl) { h16x4 s4;
; #pragma unroll
;             for (int r = 0; r < 4; ++r) s4[r] = (h16)(Sacc[vbl][r] * scal[w * 16 + fq * 4 + r]);
;             *(LAS u32x2*)(STs + w136 + (vbl * 16 * 136 + w * 16) * 2) = __builtin_bit_cast(u32x2, s4); }
; #pragma unroll
;         for (int tt = 0; tt < 2; ++tt) { const int t = 2 * w + tt, ib = t >> 2, jb = t & 3; f32x4 a = {0.f, 0.f, 0.f, 0.f};
;             if (jb <= ib) {
; #pragma unroll
;                 for (int ks = 0; ks < 4; ++ks) { const h16x8 kf = *(const LAS h16x8*)(KTs + f136 + (jb * 16 * 136 + ks * 32) * 2), qf = *(const LAS h16x8*)(QTs + f136 + (ib * 16 * 136 + ks * 32) * 2);
;                     a = __builtin_amdgcn_mfma_f32_16x16x32_f16(kf, qf, a, 0, 0, 0); }
; #pragma unroll
;                 for (int r = 0; r < 4; ++r) if (jb * 16 + fq * 4 + r > ib * 16 + fr) a[r] = 0.f;
;             }
;             h16x4 a4; a4[0] = (h16)a[0]; a4[1] = (h16)a[1]; a4[2] = (h16)a[2]; a4[3] = (h16)a[3];
;             *(LAS u32x2*)(As + w72 + (ib * 16 * 72 + jb * 16) * 2) = __builtin_bit_cast(u32x2, a4); }
.LBB0_1498:
	s_or_b64 exec, exec, s[24:25]
	s_lshl_b64 s[24:25], s[42:43], 15
	v_lshl_add_u64 v[50:51], v[144:145], 0, s[24:25]
	v_add_co_u32_e32 v18, vcc, 0x1000, v50
	v_lshl_add_u64 v[54:55], v[50:51], 0, s[36:37]
	s_nop 0
	v_addc_co_u32_e32 v19, vcc, 0, v51, vcc
	global_load_dwordx4 v[46:49], v[50:51], off
	global_load_dwordx4 v[42:45], v[50:51], off offset:64
	global_load_dwordx4 v[38:41], v[50:51], off offset:2048
	global_load_dwordx4 v[34:37], v[50:51], off offset:2112
	global_load_dwordx4 v[30:33], v[18:19], off
	global_load_dwordx4 v[26:29], v[18:19], off offset:64
	global_load_dwordx4 v[22:25], v[18:19], off offset:2048
	s_nop 0
	global_load_dwordx4 v[18:21], v[18:19], off offset:2112
	s_nop 0
	global_load_dwordx4 v[62:65], v[54:55], off
	global_load_dwordx4 v[58:61], v[54:55], off offset:64
	global_load_dwordx4 v[50:53], v[54:55], off offset:2048
	s_nop 0
	global_load_dwordx4 v[54:57], v[54:55], off offset:2112
	s_add_i32 s24, s81, s70
	v_lshl_add_u32 v178, v164, 2, s24
	s_waitcnt lgkmcnt(0)
	s_barrier
	ds_read_b128 v[204:207], v178 offset:53248
	v_add_u32_e32 v177, s81, v163
	v_add_u32_e32 v179, s67, v177
	ds_read_b128 v[228:231], v179
	ds_read_b128 v[232:235], v179 offset:64
	ds_read_b128 v[240:243], v179 offset:128
	ds_read_b128 v[244:247], v179 offset:192
	v_cndmask_b32_e64 v169, 0, 1, s[38:39]
	v_cmp_ne_u32_e64 s[26:27], 1, v169
	s_andn2_b64 vcc, exec, s[38:39]
	s_waitcnt lgkmcnt(4)
	v_pk_mul_f32 v[180:181], v[2:3], v[204:205]
	v_pk_mul_f32 v[182:183], v[4:5], v[206:207]
	v_cvt_pk_f16_f32 v180, v180, v181
	v_cvt_pk_f16_f32 v181, v182, v183
	ds_write_b64 v167, v[180:181]
	v_add_u32_e32 v169, s66, v177
	v_mov_b32_e32 v177, 0
	v_pk_mul_f32 v[208:209], v[10:11], v[204:205]
	v_pk_mul_f32 v[210:211], v[12:13], v[206:207]
	v_cvt_pk_f16_f32 v208, v208, v209
	v_cvt_pk_f16_f32 v209, v210, v211
	ds_write_b64 v167, v[208:209] offset:4352
	v_pk_mul_f32 v[180:181], v[14:15], v[204:205]
	v_pk_mul_f32 v[182:183], v[16:17], v[206:207]
	v_cvt_pk_f16_f32 v180, v180, v181
	v_cvt_pk_f16_f32 v181, v182, v183
	ds_write_b64 v167, v[180:181] offset:8704
	v_pk_mul_f32 v[208:209], v[6:7], v[204:205]
	v_pk_mul_f32 v[210:211], v[8:9], v[206:207]
	v_cvt_pk_f16_f32 v208, v208, v209
	v_cvt_pk_f16_f32 v209, v210, v211
	ds_write_b64 v167, v[208:209] offset:13056
	v_mov_b32_e32 v180, 0
	v_mov_b32_e32 v181, 0
	v_mov_b32_e32 v182, 0
	v_mov_b32_e32 v183, 0
	s_cbranch_vccnz .LBB0_1500
	ds_read_b128 v[212:215], v169 offset:17408
	ds_read_b128 v[216:219], v169 offset:17472
	ds_read_b128 v[220:223], v169 offset:17536
	ds_read_b128 v[224:227], v169 offset:17600
	s_waitcnt lgkmcnt(3)
	v_mfma_f32_16x16x32_f16 v[182:185], v[212:215], v[228:231], 0
	s_waitcnt lgkmcnt(2)
	v_mfma_f32_16x16x32_f16 v[182:185], v[216:219], v[232:235], v[182:185]
	s_waitcnt lgkmcnt(1)
	v_mfma_f32_16x16x32_f16 v[182:185], v[220:223], v[240:243], v[182:185]
	s_waitcnt lgkmcnt(0)
	v_mfma_f32_16x16x32_f16 v[182:185], v[224:227], v[244:247], v[182:185]
	v_mov_b32_e32 v186, s49
	s_nop 6
	v_cndmask_b32_e64 v177, v182, v186, s[20:21]
	v_cndmask_b32_e64 v177, v177, v182, s[16:17]
	v_cndmask_b32_e64 v181, 0, v183, s[16:17]
	v_cndmask_b32_e64 v182, v184, 0, s[18:19]
	v_cndmask_b32_e64 v183, v185, 0, s[14:15]
.LBB0_1500:
	v_cvt_pk_f16_f32 v183, v182, v183
	v_cvt_pk_f16_f32 v182, v177, v181
	v_add_u32_e32 v177, s73, v168
	v_cndmask_b32_e64 v181, 0, 1, s[40:41]
	ds_write_b64 v177, v[182:183]
	v_cmp_ne_u32_e64 s[24:25], 1, v181
	s_andn2_b64 vcc, exec, s[40:41]
	v_mov_b32_e32 v181, 0
	v_mov_b32_e32 v182, 0
	v_mov_b32_e32 v183, 0
	s_cbranch_vccnz .LBB0_1502
	ds_read_b128 v[212:215], v169 offset:21760
	ds_read_b128 v[216:219], v169 offset:21824
	ds_read_b128 v[220:223], v169 offset:21888
	ds_read_b128 v[224:227], v169 offset:21952
	s_waitcnt lgkmcnt(3)
	v_mfma_f32_16x16x32_f16 v[180:183], v[212:215], v[228:231], 0
	s_waitcnt lgkmcnt(2)
	v_mfma_f32_16x16x32_f16 v[180:183], v[216:219], v[232:235], v[180:183]
	s_waitcnt lgkmcnt(1)
	v_mfma_f32_16x16x32_f16 v[180:183], v[220:223], v[240:243], v[180:183]
	s_waitcnt lgkmcnt(0)
	v_mfma_f32_16x16x32_f16 v[180:183], v[224:227], v[244:247], v[180:183]
	v_mov_b32_e32 v184, s49
	s_nop 6
	v_cndmask_b32_e64 v169, v180, v184, s[12:13]
	v_cndmask_b32_e64 v180, v169, v180, s[8:9]
	v_cndmask_b32_e64 v181, 0, v181, s[8:9]
	v_cndmask_b32_e64 v182, v182, 0, s[10:11]
	v_cndmask_b32_e64 v183, v183, 0, s[6:7]
; #define LAS __attribute__((address_space(3)))
; __device__ __forceinline__ void gla_chain(int wv, const Args& A, LAS unsigned char* lds, int cidx0, int nsteps, int h, int sl, const float* S0, float* Sout) {
;     ...
;         __syncthreads();
;         { const int ib = w >> 1;
; #pragma unroll
;             for (int j = 0; j < 2; ++j) { const int vbl = (w & 1) * 2 + j; f32x4 o = {0.f, 0.f, 0.f, 0.f};
; #pragma unroll
;                 for (int ks = 0; ks < 4; ++ks) { const h16x8 sf = *(const LAS h16x8*)(STs + f136 + (vbl * 16 * 136 + ks * 32) * 2), qf = *(const LAS h16x8*)(QTs + f136 + (ib * 16 * 136 + ks * 32) * 2);
;                     o = __builtin_amdgcn_mfma_f32_16x16x32_f16(sf, qf, o, 0, 0, 0); }
; #pragma unroll
;                 for (int ks = 0; ks < 2; ++ks) { const h16x8 af = *(const LAS h16x8*)(As + f72 + (ib * 16 * 72 + ks * 32) * 2);
;                     o = __builtin_amdgcn_mfma_f32_16x16x32_f16(voc[j][ks], af, o, 0, 0, 0); }
;                 h16x4 o4; o4[0] = (h16)o[0]; o4[1] = (h16)o[1]; o4[2] = (h16)o[2]; o4[3] = (h16)o[3];
;                 *(u32x2*)((char*)(ws + WS_MIX) + ((tok0 + ib * 16) * DM + 1024 + h * 256 + sl * 64 + vbl * 16) * 2 + g_go) = __builtin_bit_cast(u32x2, o4); } }
; #pragma unroll
;         for (int vbl = 0; vbl < 4; ++vbl) {
; #pragma unroll
;             for (int r = 0; r < 4; ++r) Sacc[vbl][r] *= scal[128 + w * 16 + fq * 4 + r];
; #pragma unroll
;             for (int ks = 0; ks < 2; ++ks) { const h16x8 kf = *(const LAS h16x8*)(KTTs + f72 + (w * 16 * 72 + ks * 32) * 2);
;                 Sacc[vbl] = __builtin_amdgcn_mfma_f32_16x16x32_f16(kf, vc[vbl][ks], Sacc[vbl], 0, 0, 0); } }
.LBB0_1502:
	v_cvt_pk_f16_f32 v183, v182, v183
	v_cvt_pk_f16_f32 v182, v180, v181
	v_add_u32_e32 v169, s74, v168
	ds_write_b64 v169, v[182:183]
	s_waitcnt lgkmcnt(0)
	s_barrier
	ds_read_b128 v[180:183], v0
	ds_read_b128 v[188:191], v0 offset:64
	ds_read_b128 v[192:195], v0 offset:128
	ds_read_b128 v[196:199], v0 offset:192
	ds_read_b128 v[200:203], v161
	ds_read_b128 v[208:211], v161 offset:64
	ds_read_b128 v[212:215], v0 offset:4352
	ds_read_b128 v[216:219], v0 offset:4416
	ds_read_b128 v[220:223], v0 offset:4480
	ds_read_b128 v[224:227], v0 offset:4544
	s_add_u32 s43, s80, s69
	s_addc_u32 s93, 0, s31
	s_or_b32 s92, s43, 0x800
	s_waitcnt lgkmcnt(9)
	v_mfma_f32_16x16x32_f16 v[180:183], v[180:183], v[228:231], 0
	s_add_u32 s43, s43, 32
	s_addc_u32 s89, s93, 0
	s_waitcnt lgkmcnt(8)
	v_mfma_f32_16x16x32_f16 v[180:183], v[188:191], v[232:235], v[180:183]
	s_or_b32 s88, s43, 0x800
	s_add_i32 s43, s59, s81
	s_waitcnt lgkmcnt(7)
	v_mfma_f32_16x16x32_f16 v[180:183], v[192:195], v[240:243], v[180:183]
	s_add_u32 s90, s90, 0x10000
	s_addc_u32 s91, s91, 0
	s_waitcnt lgkmcnt(6)
	v_mfma_f32_16x16x32_f16 v[180:183], v[196:199], v[244:247], v[180:183]
	s_add_i32 s42, s42, 4
	s_add_u32 s69, s69, 0x40000
	s_waitcnt vmcnt(21) lgkmcnt(5)
	v_mfma_f32_16x16x32_f16 v[134:137], v[134:137], v[200:203], v[180:183]
	s_addc_u32 s31, 0, s31
	s_add_i32 s72, s72, 1
	s_waitcnt vmcnt(20) lgkmcnt(4)
	v_mfma_f32_16x16x32_f16 v[130:133], v[130:133], v[208:211], v[134:137]
	s_waitcnt lgkmcnt(3)
	v_mfma_f32_16x16x32_f16 v[184:187], v[212:215], v[228:231], 0
	v_add_u32_e32 v146, 0x200, v146
	s_waitcnt lgkmcnt(2)
	v_mfma_f32_16x16x32_f16 v[184:187], v[216:219], v[232:235], v[184:187]
	s_waitcnt lgkmcnt(1)
	v_mfma_f32_16x16x32_f16 v[184:187], v[220:223], v[240:243], v[184:187]
	s_waitcnt lgkmcnt(0)
	v_mfma_f32_16x16x32_f16 v[184:187], v[224:227], v[244:247], v[184:187]
	v_cvt_pk_f16_f32 v133, v132, v133
	v_cvt_pk_f16_f32 v132, v130, v131
	v_lshl_add_u64 v[130:131], v[138:139], 0, s[92:93]
	global_store_dwordx2 v[130:131], v[132:133], off
	s_cmp_lg_u32 s90, 0xff0000
	s_waitcnt vmcnt(20)
	v_mfma_f32_16x16x32_f16 v[126:129], v[126:129], v[200:203], v[184:187]
	s_waitcnt vmcnt(19)
	v_mfma_f32_16x16x32_f16 v[122:125], v[122:125], v[208:211], v[126:129]
	s_nop 5
	v_add_u32_e32 v126, s43, v160
	s_nop 0
	v_cvt_pk_f16_f32 v125, v124, v125
	v_cvt_pk_f16_f32 v124, v122, v123
	v_lshl_add_u64 v[122:123], v[138:139], 0, s[88:89]
	global_store_dwordx2 v[122:123], v[124:125], off
	ds_read_b128 v[122:125], v126 offset:34816
	ds_read_b128 v[126:129], v126 offset:34880
	ds_read_b128 v[130:133], v178 offset:53760
	s_waitcnt lgkmcnt(0)
	v_pk_mul_f32 v[2:3], v[2:3], v[130:131]
	v_pk_mul_f32 v[10:11], v[10:11], v[130:131]
	v_pk_mul_f32 v[14:15], v[14:15], v[130:131]
	v_pk_mul_f32 v[6:7], v[6:7], v[130:131]
	v_pk_mul_f32 v[4:5], v[4:5], v[132:133]
	v_pk_mul_f32 v[12:13], v[12:13], v[132:133]
	v_pk_mul_f32 v[16:17], v[16:17], v[132:133]
	v_pk_mul_f32 v[8:9], v[8:9], v[132:133]
	v_mfma_f32_16x16x32_f16 v[2:5], v[122:125], v[118:121], v[2:5]
	v_mfma_f32_16x16x32_f16 v[10:13], v[122:125], v[110:113], v[10:13]
	v_mfma_f32_16x16x32_f16 v[14:17], v[122:125], v[98:101], v[14:17]
	v_mfma_f32_16x16x32_f16 v[6:9], v[122:125], v[90:93], v[6:9]
	v_mfma_f32_16x16x32_f16 v[2:5], v[126:129], v[114:117], v[2:5]
	v_mfma_f32_16x16x32_f16 v[10:13], v[126:129], v[106:109], v[10:13]
	v_mfma_f32_16x16x32_f16 v[14:17], v[126:129], v[102:105], v[14:17]
	v_mfma_f32_16x16x32_f16 v[6:9], v[126:129], v[94:97], v[6:9]
	s_cbranch_scc0 .LBB0_1504
	s_waitcnt vmcnt(12)
	v_mov_b64_e32 v[116:117], v[44:45]
	v_mov_b64_e32 v[120:121], v[48:49]
	s_waitcnt vmcnt(2)
	v_mov_b64_e32 v[124:125], v[56:57]
	v_mov_b64_e32 v[128:129], v[52:53]
	v_mov_b64_e32 v[132:133], v[60:61]
	v_mov_b64_e32 v[136:137], v[64:65]
	v_mov_b64_e32 v[112:113], v[40:41]
	v_mov_b64_e32 v[108:109], v[36:37]
	v_mov_b64_e32 v[100:101], v[32:33]
	v_mov_b64_e32 v[104:105], v[28:29]
	v_mov_b64_e32 v[92:93], v[24:25]
	v_mov_b64_e32 v[96:97], v[20:21]
	v_mov_b64_e32 v[114:115], v[42:43]
	v_mov_b64_e32 v[118:119], v[46:47]
	v_mov_b64_e32 v[122:123], v[54:55]
	v_mov_b64_e32 v[126:127], v[50:51]
	v_mov_b64_e32 v[130:131], v[58:59]
	v_mov_b64_e32 v[134:135], v[62:63]
	v_mov_b64_e32 v[110:111], v[38:39]
	v_mov_b64_e32 v[106:107], v[34:35]
	v_mov_b64_e32 v[98:99], v[30:31]
	v_mov_b64_e32 v[102:103], v[26:27]
	v_mov_b64_e32 v[90:91], v[22:23]
	v_mov_b64_e32 v[94:95], v[18:19]
	s_branch .LBB0_1494
